# v89 + cross_stage_pipe: cross-attention K/V staging software-pipelined (each step's loads issued one step earlier, under the previous step's sum-of-squares butterfly)
# baseline (speedup 1.0000x reference)
.LBB0_329:
	s_ashr_i32 s8, s34, 6
	s_lshr_b32 s14, s34, 4
	s_and_b64 s[12:13], s[20:21], exec
	s_cselect_b32 s12, s17, s8
	s_cselect_b32 s8, s33, s14
	s_ashr_i32 s13, s12, 31
	s_lshl_b64 s[14:15], s[12:13], 19
	s_add_u32 s14, s69, s14
	s_addc_u32 s15, s70, s15
	s_lshl_b32 s8, s8, 7
	s_and_b32 s26, s8, 0x180
	s_lshl_b32 s8, s26, 1
	s_add_u32 s14, s14, s8
	s_addc_u32 s15, s15, 0
	v_lshl_add_u64 v[40:41], s[14:15], 0, v[16:17]
	v_lshl_add_u64 v[0:1], v[40:41], 0, v[20:21]
	s_barrier
	global_load_dwordx4 v[12:15], v[0:1], off
	global_load_dwordx4 v[4:7], v[0:1], off offset:1024
	s_waitcnt vmcnt(1)
	v_and_b32_e32 v239, 0xffff0000, v12
	v_lshlrev_b32_e32 v238, 16, v12
	v_mul_f32_e32 v239, v239, v239
	v_lshlrev_b32_e32 v240, 16, v13
	v_fmac_f32_e32 v239, v238, v238
	v_and_b32_e32 v241, 0xffff0000, v13
	v_fmac_f32_e32 v239, v240, v240
	v_lshlrev_b32_e32 v242, 16, v14
	v_fmac_f32_e32 v239, v241, v241
	v_and_b32_e32 v243, 0xffff0000, v14
	v_fmac_f32_e32 v239, v242, v242
	v_lshlrev_b32_e32 v244, 16, v15
	v_fmac_f32_e32 v239, v243, v243
	v_fmac_f32_e32 v239, v244, v244
	v_and_b32_e32 v238, 0xffff0000, v15
	v_fmac_f32_e32 v239, v238, v238
	ds_bpermute_b32 v238, v102, v239
	v_lshl_add_u64 v[0:1], v[40:41], 0, v[22:23]
	global_load_dwordx4 v[8:11], v[0:1], off
	s_nop 0
	global_load_dwordx4 v[0:3], v[0:1], off offset:1024
	s_waitcnt lgkmcnt(0)
	v_add_f32_e32 v238, v239, v238
	ds_bpermute_b32 v239, v103, v238
	s_waitcnt lgkmcnt(0)
	v_add_f32_e32 v238, v238, v239
	ds_bpermute_b32 v239, v104, v238
	s_waitcnt lgkmcnt(0)
	v_add_f32_e32 v238, v238, v239
	ds_bpermute_b32 v239, v105, v238
	s_and_saveexec_b64 s[14:15], s[0:1]
	s_cbranch_execz .LBB0_331
	s_waitcnt lgkmcnt(0)
	v_add_f32_e32 v238, v238, v239
	v_fmamk_f32 v238, v238, 0x3c000000, v132
	v_mul_f32_e32 v239, 0x4b800000, v238
	v_cmp_gt_f32_e32 vcc, s22, v238
	s_nop 1
	v_cndmask_b32_e32 v238, v238, v239, vcc
	v_rsq_f32_e32 v238, v238
	s_nop 0
	v_mul_f32_e32 v239, 0x45800000, v238
	v_cndmask_b32_e32 v238, v238, v239, vcc
	ds_write_b32 v113, v238
.LBB0_331:
	s_or_b64 exec, exec, s[14:15]
	s_waitcnt lgkmcnt(0)
	s_waitcnt vmcnt(1)
	v_and_b32_e32 v43, 0xffff0000, v8
	v_lshlrev_b32_e32 v42, 16, v8
	v_mul_f32_e32 v43, v43, v43
	v_lshlrev_b32_e32 v44, 16, v9
	v_fmac_f32_e32 v43, v42, v42
	v_and_b32_e32 v45, 0xffff0000, v9
	v_fmac_f32_e32 v43, v44, v44
	v_lshlrev_b32_e32 v46, 16, v10
	v_fmac_f32_e32 v43, v45, v45
	v_and_b32_e32 v47, 0xffff0000, v10
	v_fmac_f32_e32 v43, v46, v46
	v_lshlrev_b32_e32 v48, 16, v11
	v_fmac_f32_e32 v43, v47, v47
	v_fmac_f32_e32 v43, v48, v48
	v_and_b32_e32 v42, 0xffff0000, v11
	v_fmac_f32_e32 v43, v42, v42
	ds_bpermute_b32 v42, v102, v43
	v_add_u32_e32 v44, v106, v114
	ds_write_b128 v44, v[12:15]
	v_add_u32_e32 v12, v107, v114
	ds_write_b128 v12, v[4:7]
	v_lshl_add_u64 v[4:5], v[40:41], 0, v[24:25]
	global_load_dwordx4 v[12:15], v[4:5], off
	s_nop 0
	global_load_dwordx4 v[4:7], v[4:5], off offset:1024
	s_waitcnt lgkmcnt(2)
	v_add_f32_e32 v42, v43, v42
	ds_bpermute_b32 v43, v103, v42
	s_waitcnt lgkmcnt(0)
	v_add_f32_e32 v42, v42, v43
	ds_bpermute_b32 v43, v104, v42
	s_waitcnt lgkmcnt(0)
	v_add_f32_e32 v42, v42, v43
	ds_bpermute_b32 v43, v105, v42
	s_and_saveexec_b64 s[14:15], s[0:1]
	s_cbranch_execz .LBB0_333
	s_waitcnt lgkmcnt(0)
	v_add_f32_e32 v236, v42, v43
	v_fmamk_f32 v236, v236, 0x3c000000, v132
	v_mul_f32_e32 v237, 0x4b800000, v236
	v_cmp_gt_f32_e32 vcc, s22, v236
	s_nop 1
	v_cndmask_b32_e32 v236, v236, v237, vcc
	v_rsq_f32_e32 v236, v236
	s_nop 0
	v_mul_f32_e32 v237, 0x45800000, v236
	v_cndmask_b32_e32 v236, v236, v237, vcc
	ds_write_b32 v115, v236
.LBB0_333:
	s_or_b64 exec, exec, s[14:15]
	s_waitcnt vmcnt(1) lgkmcnt(0)
	v_and_b32_e32 v43, 0xffff0000, v12
	v_lshlrev_b32_e32 v42, 16, v12
	v_mul_f32_e32 v43, v43, v43
	v_lshlrev_b32_e32 v44, 16, v13
	v_fmac_f32_e32 v43, v42, v42
	v_and_b32_e32 v45, 0xffff0000, v13
	v_fmac_f32_e32 v43, v44, v44
	v_lshlrev_b32_e32 v46, 16, v14
	v_fmac_f32_e32 v43, v45, v45
	v_and_b32_e32 v47, 0xffff0000, v14
	v_fmac_f32_e32 v43, v46, v46
	v_lshlrev_b32_e32 v48, 16, v15
	v_fmac_f32_e32 v43, v47, v47
	v_fmac_f32_e32 v43, v48, v48
	v_and_b32_e32 v42, 0xffff0000, v15
	v_fmac_f32_e32 v43, v42, v42
	ds_bpermute_b32 v42, v102, v43
	v_add_u32_e32 v44, v106, v116
	ds_write_b128 v44, v[8:11]
	v_add_u32_e32 v8, v107, v116
	ds_write_b128 v8, v[0:3]
	v_lshl_add_u64 v[0:1], v[40:41], 0, v[26:27]
	global_load_dwordx4 v[8:11], v[0:1], off
	s_nop 0
	global_load_dwordx4 v[0:3], v[0:1], off offset:1024
	s_waitcnt lgkmcnt(2)
	v_add_f32_e32 v42, v43, v42
	ds_bpermute_b32 v43, v103, v42
	s_waitcnt lgkmcnt(0)
	v_add_f32_e32 v42, v42, v43
	ds_bpermute_b32 v43, v104, v42
	s_waitcnt lgkmcnt(0)
	v_add_f32_e32 v42, v42, v43
	ds_bpermute_b32 v43, v105, v42
	s_and_saveexec_b64 s[14:15], s[0:1]
	s_cbranch_execz .LBB0_335
	s_waitcnt lgkmcnt(0)
	v_add_f32_e32 v236, v42, v43
	v_fmamk_f32 v236, v236, 0x3c000000, v132
	v_mul_f32_e32 v237, 0x4b800000, v236
	v_cmp_gt_f32_e32 vcc, s22, v236
	s_nop 1
	v_cndmask_b32_e32 v236, v236, v237, vcc
	v_rsq_f32_e32 v236, v236
	s_nop 0
	v_mul_f32_e32 v237, 0x45800000, v236
	v_cndmask_b32_e32 v236, v236, v237, vcc
	ds_write_b32 v117, v236
.LBB0_335:
	s_or_b64 exec, exec, s[14:15]
	s_waitcnt vmcnt(1) lgkmcnt(0)
	v_and_b32_e32 v43, 0xffff0000, v8
	v_lshlrev_b32_e32 v42, 16, v8
	v_mul_f32_e32 v43, v43, v43
	v_lshlrev_b32_e32 v44, 16, v9
	v_fmac_f32_e32 v43, v42, v42
	v_and_b32_e32 v45, 0xffff0000, v9
	v_fmac_f32_e32 v43, v44, v44
	v_lshlrev_b32_e32 v46, 16, v10
	v_fmac_f32_e32 v43, v45, v45
	v_and_b32_e32 v47, 0xffff0000, v10
	v_fmac_f32_e32 v43, v46, v46
	v_lshlrev_b32_e32 v48, 16, v11
	v_fmac_f32_e32 v43, v47, v47
	v_fmac_f32_e32 v43, v48, v48
	v_and_b32_e32 v42, 0xffff0000, v11
	v_fmac_f32_e32 v43, v42, v42
	ds_bpermute_b32 v42, v102, v43
	v_add_u32_e32 v44, v106, v118
	ds_write_b128 v44, v[12:15]
	v_add_u32_e32 v12, v107, v118
	ds_write_b128 v12, v[4:7]
	v_lshl_add_u64 v[4:5], v[40:41], 0, v[28:29]
	global_load_dwordx4 v[12:15], v[4:5], off
	s_nop 0
	global_load_dwordx4 v[4:7], v[4:5], off offset:1024
	s_waitcnt lgkmcnt(2)
	v_add_f32_e32 v42, v43, v42
	ds_bpermute_b32 v43, v103, v42
	s_waitcnt lgkmcnt(0)
	v_add_f32_e32 v42, v42, v43
	ds_bpermute_b32 v43, v104, v42
	s_waitcnt lgkmcnt(0)
	v_add_f32_e32 v42, v42, v43
	ds_bpermute_b32 v43, v105, v42
	s_and_saveexec_b64 s[14:15], s[0:1]
	s_cbranch_execz .LBB0_337
	s_waitcnt lgkmcnt(0)
	v_add_f32_e32 v236, v42, v43
	v_fmamk_f32 v236, v236, 0x3c000000, v132
	v_mul_f32_e32 v237, 0x4b800000, v236
	v_cmp_gt_f32_e32 vcc, s22, v236
	s_nop 1
	v_cndmask_b32_e32 v236, v236, v237, vcc
	v_rsq_f32_e32 v236, v236
	s_nop 0
	v_mul_f32_e32 v237, 0x45800000, v236
	v_cndmask_b32_e32 v236, v236, v237, vcc
	ds_write_b32 v119, v236
.LBB0_337:
	s_or_b64 exec, exec, s[14:15]
	s_waitcnt vmcnt(1) lgkmcnt(0)
	v_and_b32_e32 v43, 0xffff0000, v12
	v_lshlrev_b32_e32 v42, 16, v12
	v_mul_f32_e32 v43, v43, v43
	v_lshlrev_b32_e32 v44, 16, v13
	v_fmac_f32_e32 v43, v42, v42
	v_and_b32_e32 v45, 0xffff0000, v13
	v_fmac_f32_e32 v43, v44, v44
	v_lshlrev_b32_e32 v46, 16, v14
	v_fmac_f32_e32 v43, v45, v45
	v_and_b32_e32 v47, 0xffff0000, v14
	v_fmac_f32_e32 v43, v46, v46
	v_lshlrev_b32_e32 v48, 16, v15
	v_fmac_f32_e32 v43, v47, v47
	v_fmac_f32_e32 v43, v48, v48
	v_and_b32_e32 v42, 0xffff0000, v15
	v_fmac_f32_e32 v43, v42, v42
	ds_bpermute_b32 v42, v102, v43
	v_add_u32_e32 v44, v106, v120
	ds_write_b128 v44, v[8:11]
	v_add_u32_e32 v8, v107, v120
	ds_write_b128 v8, v[0:3]
	v_lshl_add_u64 v[0:1], v[40:41], 0, v[30:31]
	global_load_dwordx4 v[8:11], v[0:1], off
	s_nop 0
	global_load_dwordx4 v[0:3], v[0:1], off offset:1024
	s_waitcnt lgkmcnt(2)
	v_add_f32_e32 v42, v43, v42
	ds_bpermute_b32 v43, v103, v42
	s_waitcnt lgkmcnt(0)
	v_add_f32_e32 v42, v42, v43
	ds_bpermute_b32 v43, v104, v42
	s_waitcnt lgkmcnt(0)
	v_add_f32_e32 v42, v42, v43
	ds_bpermute_b32 v43, v105, v42
	s_and_saveexec_b64 s[14:15], s[0:1]
	s_cbranch_execz .LBB0_339
	s_waitcnt lgkmcnt(0)
	v_add_f32_e32 v236, v42, v43
	v_fmamk_f32 v236, v236, 0x3c000000, v132
	v_mul_f32_e32 v237, 0x4b800000, v236
	v_cmp_gt_f32_e32 vcc, s22, v236
	s_nop 1
	v_cndmask_b32_e32 v236, v236, v237, vcc
	v_rsq_f32_e32 v236, v236
	s_nop 0
	v_mul_f32_e32 v237, 0x45800000, v236
	v_cndmask_b32_e32 v236, v236, v237, vcc
	ds_write_b32 v121, v236
.LBB0_339:
	s_or_b64 exec, exec, s[14:15]
	s_waitcnt vmcnt(1) lgkmcnt(0)
	v_and_b32_e32 v43, 0xffff0000, v8
	v_lshlrev_b32_e32 v42, 16, v8
	v_mul_f32_e32 v43, v43, v43
	v_lshlrev_b32_e32 v44, 16, v9
	v_fmac_f32_e32 v43, v42, v42
	v_and_b32_e32 v45, 0xffff0000, v9
	v_fmac_f32_e32 v43, v44, v44
	v_lshlrev_b32_e32 v46, 16, v10
	v_fmac_f32_e32 v43, v45, v45
	v_and_b32_e32 v47, 0xffff0000, v10
	v_fmac_f32_e32 v43, v46, v46
	v_lshlrev_b32_e32 v48, 16, v11
	v_fmac_f32_e32 v43, v47, v47
	v_fmac_f32_e32 v43, v48, v48
	v_and_b32_e32 v42, 0xffff0000, v11
	v_fmac_f32_e32 v43, v42, v42
	ds_bpermute_b32 v42, v102, v43
	v_add_u32_e32 v44, v106, v122
	ds_write_b128 v44, v[12:15]
	v_add_u32_e32 v12, v107, v122
	ds_write_b128 v12, v[4:7]
	v_lshl_add_u64 v[4:5], v[40:41], 0, v[32:33]
	global_load_dwordx4 v[12:15], v[4:5], off
	s_nop 0
	global_load_dwordx4 v[4:7], v[4:5], off offset:1024
	s_waitcnt lgkmcnt(2)
	v_add_f32_e32 v42, v43, v42
	ds_bpermute_b32 v43, v103, v42
	s_waitcnt lgkmcnt(0)
	v_add_f32_e32 v42, v42, v43
	ds_bpermute_b32 v43, v104, v42
	s_waitcnt lgkmcnt(0)
	v_add_f32_e32 v42, v42, v43
	ds_bpermute_b32 v43, v105, v42
	s_and_saveexec_b64 s[14:15], s[0:1]
	s_cbranch_execz .LBB0_341
	s_waitcnt lgkmcnt(0)
	v_add_f32_e32 v236, v42, v43
	v_fmamk_f32 v236, v236, 0x3c000000, v132
	v_mul_f32_e32 v237, 0x4b800000, v236
	v_cmp_gt_f32_e32 vcc, s22, v236
	s_nop 1
	v_cndmask_b32_e32 v236, v236, v237, vcc
	v_rsq_f32_e32 v236, v236
	s_nop 0
	v_mul_f32_e32 v237, 0x45800000, v236
	v_cndmask_b32_e32 v236, v236, v237, vcc
	ds_write_b32 v123, v236
.LBB0_341:
	s_or_b64 exec, exec, s[14:15]
	s_waitcnt vmcnt(1) lgkmcnt(0)
	v_and_b32_e32 v43, 0xffff0000, v12
	v_lshlrev_b32_e32 v42, 16, v12
	v_mul_f32_e32 v43, v43, v43
	v_lshlrev_b32_e32 v44, 16, v13
	v_fmac_f32_e32 v43, v42, v42
	v_and_b32_e32 v45, 0xffff0000, v13
	v_fmac_f32_e32 v43, v44, v44
	v_lshlrev_b32_e32 v46, 16, v14
	v_fmac_f32_e32 v43, v45, v45
	v_and_b32_e32 v47, 0xffff0000, v14
	v_fmac_f32_e32 v43, v46, v46
	v_lshlrev_b32_e32 v48, 16, v15
	v_fmac_f32_e32 v43, v47, v47
	v_fmac_f32_e32 v43, v48, v48
	v_and_b32_e32 v42, 0xffff0000, v15
	v_fmac_f32_e32 v43, v42, v42
	ds_bpermute_b32 v42, v102, v43
	v_add_u32_e32 v44, v106, v124
	ds_write_b128 v44, v[8:11]
	v_add_u32_e32 v8, v107, v124
	ds_write_b128 v8, v[0:3]
	v_lshl_add_u64 v[0:1], v[40:41], 0, v[34:35]
	global_load_dwordx4 v[8:11], v[0:1], off
	s_nop 0
	global_load_dwordx4 v[0:3], v[0:1], off offset:1024
	s_waitcnt lgkmcnt(2)
	v_add_f32_e32 v42, v43, v42
	ds_bpermute_b32 v43, v103, v42
	s_waitcnt lgkmcnt(0)
	v_add_f32_e32 v42, v42, v43
	ds_bpermute_b32 v43, v104, v42
	s_waitcnt lgkmcnt(0)
	v_add_f32_e32 v42, v42, v43
	ds_bpermute_b32 v43, v105, v42
	s_and_saveexec_b64 s[14:15], s[0:1]
	s_cbranch_execz .LBB0_343
	s_waitcnt lgkmcnt(0)
	v_add_f32_e32 v236, v42, v43
	v_fmamk_f32 v236, v236, 0x3c000000, v132
	v_mul_f32_e32 v237, 0x4b800000, v236
	v_cmp_gt_f32_e32 vcc, s22, v236
	s_nop 1
	v_cndmask_b32_e32 v236, v236, v237, vcc
	v_rsq_f32_e32 v236, v236
	s_nop 0
	v_mul_f32_e32 v237, 0x45800000, v236
	v_cndmask_b32_e32 v236, v236, v237, vcc
	ds_write_b32 v125, v236
.LBB0_343:
	s_or_b64 exec, exec, s[14:15]
	s_waitcnt vmcnt(1)
	v_and_b32_e32 v41, 0xffff0000, v8
	v_lshlrev_b32_e32 v40, 16, v8
	v_mul_f32_e32 v41, v41, v41
	v_lshlrev_b32_e32 v42, 16, v9
	v_fmac_f32_e32 v41, v40, v40
	s_waitcnt lgkmcnt(0)
	v_and_b32_e32 v43, 0xffff0000, v9
	v_fmac_f32_e32 v41, v42, v42
	v_lshlrev_b32_e32 v44, 16, v10
	v_fmac_f32_e32 v41, v43, v43
	v_and_b32_e32 v45, 0xffff0000, v10
	v_fmac_f32_e32 v41, v44, v44
	v_lshlrev_b32_e32 v46, 16, v11
	v_fmac_f32_e32 v41, v45, v45
	v_fmac_f32_e32 v41, v46, v46
	v_and_b32_e32 v40, 0xffff0000, v11
	v_fmac_f32_e32 v41, v40, v40
	ds_bpermute_b32 v40, v102, v41
	v_add_u32_e32 v42, v106, v126
	ds_write_b128 v42, v[12:15]
	v_add_u32_e32 v12, v107, v126
	ds_write_b128 v12, v[4:7]
	s_waitcnt lgkmcnt(2)
	v_add_f32_e32 v40, v41, v40
	ds_bpermute_b32 v41, v103, v40
	s_waitcnt lgkmcnt(0)
	v_add_f32_e32 v40, v40, v41
	ds_bpermute_b32 v41, v104, v40
	s_waitcnt lgkmcnt(0)
	v_add_f32_e32 v40, v40, v41
	ds_bpermute_b32 v41, v105, v40
	s_and_saveexec_b64 s[14:15], s[0:1]
	s_cbranch_execz .LBB0_345
	s_waitcnt lgkmcnt(0)
	v_add_f32_e32 v4, v40, v41
	v_fmamk_f32 v4, v4, 0x3c000000, v132
	v_mul_f32_e32 v5, 0x4b800000, v4
	v_cmp_gt_f32_e32 vcc, s22, v4
	s_nop 1
	v_cndmask_b32_e32 v4, v4, v5, vcc
	v_rsq_f32_e32 v4, v4
	s_nop 0
	v_mul_f32_e32 v5, 0x45800000, v4
	v_cndmask_b32_e32 v4, v4, v5, vcc
	ds_write_b32 v127, v4
